# stacked small edits: BTY setup loop issues both Toeplitz loads before one wait and hoists its kernarg s_load; attention K/V prefetch loads use scalar base + 32-bit lane offset (no per-stage 64-bit VAL
# baseline (speedup 1.0000x reference)
.LBB0_19:
	s_or_b64 exec, exec, s[18:19]
	s_mov_b32 s2, 0x800000
	v_cmp_gt_i32_e32 vcc, s2, v6
	s_waitcnt lgkmcnt(0)
	s_and_saveexec_b64 s[8:9], vcc
	s_cbranch_execz .LBB0_378
	v_and_b32_e32 v1, 0x1ff, v12
	s_add_u32 s10, s14, 0x7880000
	v_subrev_co_u32_e32 v3, vcc, 0x100, v1
	s_movk_i32 s2, 0x80
	s_addc_u32 s11, s15, 0
	s_xor_b64 s[18:19], vcc, -1
	v_lshrrev_b32_e32 v1, 3, v3
	v_cmp_gt_u32_e32 vcc, s2, v3
	v_lshl_add_u64 v[8:9], v[6:7], 1, s[14:15]
	s_mov_b64 s[2:3], 0x6880000
	s_ashr_i32 s13, s12, 31
	v_and_b32_e32 v4, 63, v12
	v_and_b32_e32 v1, 0x1ffffff0, v1
	v_mov_b32_e32 v3, 0
	v_bfe_u32 v5, v12, 4, 5
	v_lshl_add_u64 v[8:9], v[8:9], 0, s[2:3]
	s_lshl_b64 s[14:15], s[12:13], 1
	s_mov_b64 s[20:21], 0
	s_movk_i32 s2, 0xffe0
	s_mov_b32 s3, 0x7fffff
	v_lshlrev_b32_e32 v10, 2, v2
	s_load_dwordx4 s[24:27], s[6:7], 0xa8
	s_waitcnt lgkmcnt(0)
	s_branch .LBB0_23

.LBB0_23:
	v_bfe_u32 v2, v6, 17, 4
	v_bfe_u32 v7, v6, 13, 4
	v_bfe_u32 v11, v6, 9, 4
	v_and_b32_sdwa v12, sext(v6), s2 dst_sel:DWORD dst_unused:UNUSED_PAD src0_sel:WORD_1 src1_sel:DWORD
	s_and_saveexec_b64 s[4:5], s[18:19]
	s_xor_b64 s[22:23], exec, s[4:5]
	s_cbranch_execz .LBB0_25
	v_add_u32_e32 v12, v12, v1
	v_or_b32_e32 v12, v12, v2
	v_add_u32_e32 v2, 1, v7
	v_sub_u32_e32 v7, 16, v7
	v_lshl_or_b32 v13, v12, 6, v4
	v_cndmask_b32_e32 v2, v7, v2, vcc
	v_mad_i64_i32 v[14:15], s[4:5], v13, 17, v[2:3]
	v_ashrrev_i32_e32 v13, 31, v12
	v_lshlrev_b64 v[12:13], 10, v[12:13]
	v_lshl_or_b32 v2, v11, 6, v12
	v_or_b32_e32 v12, v2, v4
	v_lshlrev_b64 v[12:13], 2, v[12:13]
	v_lshl_add_u64 v[16:17], s[24:25], 0, v[12:13]
	v_lshl_add_u64 v[12:13], s[26:27], 0, v[12:13]
	v_lshl_add_u64 v[14:15], v[14:15], 3, s[16:17]
	global_load_dword v17, v[16:17], off
	s_nop 0
	global_load_dword v16, v[12:13], off
	global_load_dwordx2 v[18:19], v[14:15], off
	v_and_b32_e32 v2, 64, v6
	v_cmp_eq_u32_e64 s[4:5], 0, v2
	s_waitcnt vmcnt(0)
	v_mov_b32_e32 v15, v16
	v_pk_mul_f32 v[12:13], v[18:19], v[16:17]
	v_mov_b32_e32 v14, v17
	v_add_f32_e32 v7, v13, v12
	v_pk_mul_f32 v[12:13], v[18:19], v[14:15]
	s_nop 0
	v_sub_f32_e32 v11, v12, v13
	v_cndmask_b32_e64 v13, -v7, v11, s[4:5]
.LBB0_25:
	s_andn2_saveexec_b64 s[22:23], s[22:23]
	s_cbranch_execz .LBB0_22
	v_lshlrev_b32_e32 v11, 4, v11
	v_or_b32_e32 v12, v12, v2
	v_cmp_le_u32_e64 s[4:5], v5, v7
	v_lshlrev_b32_e32 v2, 2, v11
	v_mov_b32_e32 v18, 0
	v_mov_b32_e32 v19, 0
	s_and_saveexec_b64 s[24:25], s[4:5]
	s_cbranch_execz .Lbty_a
	v_ashrrev_i32_e32 v13, 31, v12
	v_lshlrev_b64 v[14:15], 14, v[12:13]
	v_lshl_add_u64 v[14:15], s[10:11], 0, v[14:15]
	v_lshl_add_u64 v[14:15], v[14:15], 0, v[2:3]
	v_mov_b32_e32 v11, v3
	v_lshl_add_u64 v[14:15], v[14:15], 0, v[10:11]
	v_sub_u32_e32 v11, v7, v5
	v_lshlrev_b32_e32 v16, 10, v11
	v_mov_b32_e32 v17, v3
	v_lshl_add_u64 v[14:15], v[14:15], 0, v[16:17]
	global_load_dword v18, v[14:15], off
.Lbty_a:
	s_or_b64 exec, exec, s[24:25]
	v_cmp_ge_u32_e64 s[4:5], v5, v7
	s_and_saveexec_b64 s[24:25], s[4:5]
	s_cbranch_execz .Lbty_b
	v_or_b32_e32 v14, 16, v12
	v_ashrrev_i32_e32 v15, 31, v14
	v_lshlrev_b64 v[14:15], 14, v[14:15]
	v_lshl_add_u64 v[14:15], s[10:11], 0, v[14:15]
	v_lshl_add_u64 v[14:15], v[14:15], 0, v[2:3]
	v_mov_b32_e32 v11, v3
	v_sub_u32_e32 v2, v5, v7
	v_lshl_add_u64 v[14:15], v[14:15], 0, v[10:11]
	v_lshlrev_b32_e32 v2, 10, v2
	v_lshl_add_u64 v[14:15], v[14:15], 0, v[2:3]
	global_load_dword v19, v[14:15], off
.Lbty_b:
	s_or_b64 exec, exec, s[24:25]
	s_waitcnt vmcnt(0)
	v_add_f32_e32 v13, 0, v18
	v_add_f32_e32 v13, v13, v19
	s_branch .LBB0_21

.LBB0_745:
	s_cmp_lt_i32 s8, s6
	s_mul_i32 s2, s8, s3
	s_cselect_b32 s2, s2, 0x180
	s_add_i32 s2, s2, s0
	s_ashr_i32 s10, s2, 3
	s_lshl_b32 s9, s10, 8
	s_lshl_b32 s2, s2, 6
	s_add_i32 s11, s9, 0x100
	s_and_b32 s9, s2, 0x1c0
	s_lshl_b32 s64, s9, 1
	s_cmp_lt_i32 s10, 64
	s_cselect_b32 s2, s11, 0
	v_add_u32_e32 v216, s2, v234
	v_ashrrev_i32_e32 v217, 31, v216
	v_lshlrev_b64 v[2:3], 10, v[216:217]
	v_lshl_add_u64 v[2:3], s[4:5], 0, v[2:3]
	v_lshl_add_u64 v[2:3], v[2:3], 0, s[64:65]
	v_lshl_add_u64 v[218:219], v[206:207], 0, s[64:65]
	v_lshl_add_u64 v[2:3], v[2:3], 0, v[190:191]
	v_add_co_u32_e32 v6, vcc, s83, v218
	global_load_dwordx4 v[134:137], v[2:3], off
	global_load_dwordx4 v[138:141], v[2:3], off offset:32
	global_load_dwordx4 v[142:145], v[2:3], off offset:64
	global_load_dwordx4 v[146:149], v[2:3], off offset:96
	v_lshl_add_u64 v[220:221], v[208:209], 0, s[64:65]
	global_load_dwordx4 v[2:5], v[218:219], off
	v_addc_co_u32_e32 v7, vcc, 0, v219, vcc
	global_load_dwordx4 v[6:9], v[6:7], off
	s_nop 0
	global_load_dwordx4 v[10:13], v[220:221], off
	v_add_co_u32_e32 v14, vcc, s83, v220
	s_mov_b32 s2, 0x20000
	s_nop 0
	v_addc_co_u32_e32 v15, vcc, 0, v221, vcc
	global_load_dwordx4 v[14:17], v[14:15], off
	s_barrier
	s_mov_b32 s10, 0x30000
	v_mov_b32_e32 v166, 0
	s_mov_b32 s12, 0
	s_mov_b32 s14, 0
	v_mov_b32_e32 v167, v166
	v_mov_b32_e32 v168, v166
	v_mov_b32_e32 v169, v166
	v_mov_b32_e32 v170, v166
	v_mov_b32_e32 v171, v166
	v_mov_b32_e32 v172, v166
	v_mov_b32_e32 v173, v166
	v_mov_b32_e32 v34, v166
	v_mov_b32_e32 v35, v166
	v_mov_b32_e32 v36, v166
	v_mov_b32_e32 v37, v166
	v_mov_b32_e32 v38, v166
	v_mov_b32_e32 v39, v166
	v_mov_b32_e32 v40, v166
	v_mov_b32_e32 v41, v166
	v_mov_b32_e32 v42, v166
	v_mov_b32_e32 v43, v166
	v_mov_b32_e32 v44, v166
	v_mov_b32_e32 v45, v166
	v_mov_b32_e32 v46, v166
	v_mov_b32_e32 v47, v166
	v_mov_b32_e32 v48, v166
	v_mov_b32_e32 v49, v166
	v_mov_b32_e32 v18, v166
	v_mov_b32_e32 v19, v166
	v_mov_b32_e32 v20, v166
	v_mov_b32_e32 v21, v166
	v_mov_b32_e32 v22, v166
	v_mov_b32_e32 v23, v166
	v_mov_b32_e32 v24, v166
	v_mov_b32_e32 v25, v166
	v_mov_b32_e32 v26, v166
	v_mov_b32_e32 v27, v166
	v_mov_b32_e32 v28, v166
	v_mov_b32_e32 v29, v166
	v_mov_b32_e32 v30, v166
	v_mov_b32_e32 v31, v166
	v_mov_b32_e32 v32, v166
	v_mov_b32_e32 v33, v166
	v_mov_b32_e32 v50, v166
	v_mov_b32_e32 v51, v166
	v_mov_b32_e32 v52, v166
	v_mov_b32_e32 v53, v166
	v_mov_b32_e32 v54, v166
	v_mov_b32_e32 v55, v166
	v_mov_b32_e32 v56, v166
	v_mov_b32_e32 v57, v166
	v_mov_b32_e32 v58, v166
	v_mov_b32_e32 v59, v166
	v_mov_b32_e32 v60, v166
	v_mov_b32_e32 v61, v166
	v_mov_b32_e32 v62, v166
	v_mov_b32_e32 v63, v166
	v_mov_b32_e32 v64, v166
	v_mov_b32_e32 v65, v166
	s_waitcnt vmcnt(3)
	ds_write_b128 v235, v[2:5]
	s_waitcnt vmcnt(2)
	ds_write_b128 v235, v[6:9] offset:9216
	v_add_u32_e32 v2, v235, v205
	s_waitcnt vmcnt(1)
	ds_write_b128 v2, v[10:13] offset:55296
	v_add_u32_e32 v2, 0, v231
	v_add_u32_e32 v2, 0x10800, v2
	v_mov_b32_e32 v10, v166
	v_mov_b32_e32 v11, v166
	s_waitcnt vmcnt(0)
	ds_write_b128 v2, v[14:17]
	v_add_co_u32_e32 v2, vcc, s2, v218
	v_mov_b32_e32 v12, v166
	s_nop 0
	v_addc_co_u32_e32 v3, vcc, 0, v219, vcc
	global_load_dwordx4 v[158:161], v[2:3], off
	v_add_co_u32_e32 v2, vcc, s10, v218
	v_mov_b32_e32 v13, v166
	s_nop 0
	v_addc_co_u32_e32 v3, vcc, 0, v219, vcc
	global_load_dwordx4 v[162:165], v[2:3], off
	v_add_co_u32_e32 v2, vcc, s2, v220
	v_mov_b32_e32 v14, v166
	s_nop 0
	v_addc_co_u32_e32 v3, vcc, 0, v221, vcc
	global_load_dwordx4 v[150:153], v[2:3], off
	v_add_co_u32_e32 v2, vcc, s10, v220
	s_cselect_b32 s10, 0x82, 2
	s_nop 0
	v_addc_co_u32_e32 v3, vcc, 0, v221, vcc
	global_load_dwordx4 v[154:157], v[2:3], off
	s_waitcnt lgkmcnt(0)
	s_barrier
	ds_read_b128 v[2:5], v211
	ds_read_b128 v[6:9], v211 offset:32
	s_waitcnt lgkmcnt(1)
	v_mfma_f32_32x32x16_bf16 v[66:81], v[2:5], v[134:137], 0
	s_add_i32 s11, s10, -1
	v_mov_b32_e32 v15, v166
	v_mov_b32_e32 v16, v166
	v_mov_b32_e32 v17, v166
	s_waitcnt lgkmcnt(0)
	v_mfma_f32_32x32x16_bf16 v[66:81], v[6:9], v[138:141], v[66:81]
	ds_read_b128 v[2:5], v211 offset:64
	ds_read_b128 v[6:9], v211 offset:96
	s_waitcnt lgkmcnt(1)
	v_mfma_f32_32x32x16_bf16 v[82:97], v[2:5], v[142:145], 0
	v_mov_b32_e32 v2, v166
	v_mov_b32_e32 v3, v166
	v_mov_b32_e32 v4, v166
	v_mov_b32_e32 v5, v166
	s_waitcnt lgkmcnt(0)
	v_mfma_f32_32x32x16_bf16 v[82:97], v[6:9], v[146:149], v[82:97]
	v_mov_b32_e32 v6, v166
	v_mov_b32_e32 v7, v166
	v_mov_b32_e32 v8, v166
	v_mov_b32_e32 v9, v166
	s_lshl_b32 s13, s9, 1
	s_add_u32 s100, s54, 0xd124000
	s_addc_u32 s101, s55, 0
	s_add_u32 s100, s100, s13
	s_addc_u32 s101, s101, 0
	v_subrev_u32_e32 v248, s100, v218
	v_add_u32_e32 v249, 0x10000, v248
	s_waitcnt lgkmcnt(0)
	v_add_u32_e32 v251, v236, v210
	v_add_u32_e32 v215, 0xd800, v232
	v_mov_b32_e32 v118, 0
	v_mov_b32_e32 v119, 0
	v_mov_b32_e32 v120, 0
	v_mov_b32_e32 v121, 0
	ds_read_b128 v[238:241], v251 offset:4608
	ds_read_b128 v[242:245], v251 offset:4640
	ds_read_b64_tr_b16 v[174:175], v215
	ds_read_b64_tr_b16 v[176:177], v215 offset:1536
	ds_read_b64_tr_b16 v[178:179], v215 offset:64
	ds_read_b64_tr_b16 v[180:181], v215 offset:1600
	v_mov_b32_e32 v182, 0
	v_mov_b32_e32 v183, 0
	v_mov_b32_e32 v184, 0
	v_mov_b32_e32 v185, 0
	v_mov_b32_e32 v186, 0
	v_mov_b32_e32 v187, 0
	v_mov_b32_e32 v188, 0
	v_mov_b32_e32 v189, 0
	s_waitcnt lgkmcnt(0)
.Latt_loop:
	s_add_i32 s13, s12, 1
	s_cmp_eq_u32 s12, 2
	s_cselect_b32 s12, 0, s13
	s_mul_i32 s15, s12, 0x4800
	s_mul_i32 s16, s12, 0x6000
	s_add_i32 s16, s16, 0xd800
	s_add_i32 s17, s14, 2
	s_min_u32 s17, s17, s11
	s_lshl_b32 s64, s17, 17
	s_add_u32 s18, s64, s83
	s_mov_b32 s19, 0
	s_add_i32 s14, s14, 1
	v_mov_b32_e32 v250, v251
	v_add3_u32 v251, s15, v236, v210
	v_mov_b32_e32 v252, v215
	v_add_u32_e32 v215, s16, v232
	s_waitcnt lgkmcnt(5)
	v_mfma_f32_32x32x16_bf16 v[98:113], v[238:241], v[134:137], 0
	ds_read_b128 v[238:241], v250 offset:4672
	v_exp_f32_e32 v66, v66
	v_exp_f32_e32 v67, v67
	v_exp_f32_e32 v68, v68
	v_mfma_f32_32x32x16_bf16 v[34:49], v[182:185], v[118:121], v[34:49]
	v_exp_f32_e32 v69, v69
	v_exp_f32_e32 v70, v70
	v_exp_f32_e32 v71, v71
	v_mfma_f32_32x32x16_bf16 v[50:65], v[186:189], v[118:121], v[50:65]
	ds_read_b64_tr_b16 v[182:183], v252 offset:3072
	ds_read_b64_tr_b16 v[184:185], v252 offset:4608
	ds_read_b64_tr_b16 v[186:187], v252 offset:3136
	ds_read_b64_tr_b16 v[188:189], v252 offset:4672
	v_exp_f32_e32 v72, v72
	v_exp_f32_e32 v73, v73
	v_cvt_pk_bf16_f32 v66, v66, v67
	v_cvt_pk_bf16_f32 v67, v68, v69
	v_mfma_f32_16x16x32_bf16 v[170:173], v[130:133], v[118:121], v[170:173]
	v_cvt_pk_bf16_f32 v68, v70, v71
	v_cvt_pk_bf16_f32 v69, v72, v73
	s_waitcnt vmcnt(0)
	v_add_u32_e32 v246, s15, v204
	v_add_u32_e32 v247, s16, v231
	ds_write_b128 v246, v[158:161]
	ds_write_b128 v246, v[162:165] offset:9216
	ds_write_b128 v247, v[150:153]
	ds_write_b128 v247, v[154:157] offset:12288
	s_add_u32 s18, s100, s64
	s_addc_u32 s19, s101, 0
	global_load_dwordx4 v[158:161], v248, s[18:19]
	global_load_dwordx4 v[162:165], v249, s[18:19]
	s_add_u32 s18, s18, 0x1040000
	s_addc_u32 s19, s19, 0
	global_load_dwordx4 v[150:153], v248, s[18:19]
	global_load_dwordx4 v[154:157], v249, s[18:19]
	s_waitcnt lgkmcnt(9)
	v_mfma_f32_32x32x16_bf16 v[98:113], v[242:245], v[138:141], v[98:113]
	ds_read_b128 v[242:245], v250 offset:4704
	v_exp_f32_e32 v82, v82
	v_exp_f32_e32 v83, v83
	v_exp_f32_e32 v84, v84
	v_mfma_f32_32x32x16_bf16 v[2:17], v[174:177], v[66:69], v[2:17]
	v_exp_f32_e32 v85, v85
	v_exp_f32_e32 v86, v86
	v_exp_f32_e32 v87, v87
	v_mfma_f32_32x32x16_bf16 v[18:33], v[178:181], v[66:69], v[18:33]
	v_exp_f32_e32 v88, v88
	v_exp_f32_e32 v89, v89
	v_cvt_pk_bf16_f32 v82, v82, v83
	v_cvt_pk_bf16_f32 v83, v84, v85
	v_mfma_f32_16x16x32_bf16 v[166:169], v[130:133], v[66:69], v[166:169]
	v_cvt_pk_bf16_f32 v84, v86, v87
	v_cvt_pk_bf16_f32 v85, v88, v89
	s_waitcnt lgkmcnt(9)
	v_mfma_f32_32x32x16_bf16 v[114:129], v[238:241], v[142:145], 0
	ds_read_b128 v[238:241], v250 offset:9216
	v_exp_f32_e32 v74, v74
	v_exp_f32_e32 v75, v75
	v_exp_f32_e32 v76, v76
	v_mfma_f32_32x32x16_bf16 v[34:49], v[174:177], v[82:85], v[34:49]
	v_exp_f32_e32 v77, v77
	v_exp_f32_e32 v78, v78
	v_exp_f32_e32 v79, v79
	v_mfma_f32_32x32x16_bf16 v[50:65], v[178:181], v[82:85], v[50:65]
	ds_read_b64_tr_b16 v[174:175], v252 offset:6144
	ds_read_b64_tr_b16 v[176:177], v252 offset:7680
	ds_read_b64_tr_b16 v[178:179], v252 offset:6208
	ds_read_b64_tr_b16 v[180:181], v252 offset:7744
	v_exp_f32_e32 v80, v80
	v_exp_f32_e32 v81, v81
	v_cvt_pk_bf16_f32 v70, v74, v75
	v_cvt_pk_bf16_f32 v71, v76, v77
	v_mfma_f32_16x16x32_bf16 v[170:173], v[130:133], v[82:85], v[170:173]
	v_cvt_pk_bf16_f32 v72, v78, v79
	v_cvt_pk_bf16_f32 v73, v80, v81
	s_waitcnt lgkmcnt(5)
	v_mfma_f32_32x32x16_bf16 v[114:129], v[242:245], v[146:149], v[114:129]
	ds_read_b128 v[242:245], v250 offset:9248
	v_exp_f32_e32 v90, v90
	v_exp_f32_e32 v91, v91
	v_exp_f32_e32 v92, v92
	v_mfma_f32_32x32x16_bf16 v[2:17], v[182:185], v[70:73], v[2:17]
	v_exp_f32_e32 v93, v93
	v_exp_f32_e32 v94, v94
	v_exp_f32_e32 v95, v95
	v_mfma_f32_32x32x16_bf16 v[18:33], v[186:189], v[70:73], v[18:33]
	v_exp_f32_e32 v96, v96
	v_exp_f32_e32 v97, v97
	v_cvt_pk_bf16_f32 v86, v90, v91
	v_cvt_pk_bf16_f32 v87, v92, v93
	v_mfma_f32_16x16x32_bf16 v[166:169], v[130:133], v[70:73], v[166:169]
	v_cvt_pk_bf16_f32 v88, v94, v95
	v_cvt_pk_bf16_f32 v89, v96, v97
	s_waitcnt lgkmcnt(5)
	v_mfma_f32_32x32x16_bf16 v[66:81], v[238:241], v[134:137], 0
	ds_read_b128 v[238:241], v250 offset:9280
	v_exp_f32_e32 v98, v98
	v_exp_f32_e32 v99, v99
	v_exp_f32_e32 v100, v100
	v_mfma_f32_32x32x16_bf16 v[34:49], v[182:185], v[86:89], v[34:49]
	v_exp_f32_e32 v101, v101
	v_exp_f32_e32 v102, v102
	v_exp_f32_e32 v103, v103
	v_mfma_f32_32x32x16_bf16 v[50:65], v[186:189], v[86:89], v[50:65]
	ds_read_b64_tr_b16 v[182:183], v252 offset:9216
	ds_read_b64_tr_b16 v[184:185], v252 offset:10752
	ds_read_b64_tr_b16 v[186:187], v252 offset:9280
	ds_read_b64_tr_b16 v[188:189], v252 offset:10816
	v_exp_f32_e32 v104, v104
	v_exp_f32_e32 v105, v105
	v_cvt_pk_bf16_f32 v98, v98, v99
	v_cvt_pk_bf16_f32 v99, v100, v101
	v_mfma_f32_16x16x32_bf16 v[170:173], v[130:133], v[86:89], v[170:173]
	v_cvt_pk_bf16_f32 v100, v102, v103
	v_cvt_pk_bf16_f32 v101, v104, v105
	s_waitcnt lgkmcnt(5)
	v_mfma_f32_32x32x16_bf16 v[66:81], v[242:245], v[138:141], v[66:81]
	ds_read_b128 v[242:245], v250 offset:9312
	v_exp_f32_e32 v114, v114
	v_exp_f32_e32 v115, v115
	v_exp_f32_e32 v116, v116
	v_mfma_f32_32x32x16_bf16 v[2:17], v[174:177], v[98:101], v[2:17]
	v_exp_f32_e32 v117, v117
	v_exp_f32_e32 v118, v118
	v_exp_f32_e32 v119, v119
	v_mfma_f32_32x32x16_bf16 v[18:33], v[178:181], v[98:101], v[18:33]
	v_exp_f32_e32 v120, v120
	v_exp_f32_e32 v121, v121
	v_cvt_pk_bf16_f32 v114, v114, v115
	v_cvt_pk_bf16_f32 v115, v116, v117
	v_mfma_f32_16x16x32_bf16 v[166:169], v[130:133], v[98:101], v[166:169]
	v_cvt_pk_bf16_f32 v116, v118, v119
	v_cvt_pk_bf16_f32 v117, v120, v121
	s_waitcnt lgkmcnt(5)
	v_mfma_f32_32x32x16_bf16 v[82:97], v[238:241], v[142:145], 0
	ds_read_b128 v[238:241], v250 offset:13824
	v_exp_f32_e32 v106, v106
	v_exp_f32_e32 v107, v107
	v_exp_f32_e32 v108, v108
	v_mfma_f32_32x32x16_bf16 v[34:49], v[174:177], v[114:117], v[34:49]
	v_exp_f32_e32 v109, v109
	v_exp_f32_e32 v110, v110
	v_exp_f32_e32 v111, v111
	v_mfma_f32_32x32x16_bf16 v[50:65], v[178:181], v[114:117], v[50:65]
	ds_read_b64_tr_b16 v[174:175], v252 offset:12288
	ds_read_b64_tr_b16 v[176:177], v252 offset:13824
	ds_read_b64_tr_b16 v[178:179], v252 offset:12352
	ds_read_b64_tr_b16 v[180:181], v252 offset:13888
	v_exp_f32_e32 v112, v112
	v_exp_f32_e32 v113, v113
	v_cvt_pk_bf16_f32 v102, v106, v107
	v_cvt_pk_bf16_f32 v103, v108, v109
	v_mfma_f32_16x16x32_bf16 v[170:173], v[130:133], v[114:117], v[170:173]
	v_cvt_pk_bf16_f32 v104, v110, v111
	v_cvt_pk_bf16_f32 v105, v112, v113
	s_waitcnt lgkmcnt(5)
	v_mfma_f32_32x32x16_bf16 v[82:97], v[242:245], v[146:149], v[82:97]
	ds_read_b128 v[242:245], v250 offset:13856
	v_exp_f32_e32 v122, v122
	v_exp_f32_e32 v123, v123
	v_exp_f32_e32 v124, v124
	v_mfma_f32_32x32x16_bf16 v[2:17], v[182:185], v[102:105], v[2:17]
	v_exp_f32_e32 v125, v125
	v_exp_f32_e32 v126, v126
	v_exp_f32_e32 v127, v127
	v_mfma_f32_32x32x16_bf16 v[18:33], v[186:189], v[102:105], v[18:33]
	v_exp_f32_e32 v128, v128
	v_exp_f32_e32 v129, v129
	v_cvt_pk_bf16_f32 v118, v122, v123
	v_cvt_pk_bf16_f32 v119, v124, v125
	v_mfma_f32_16x16x32_bf16 v[166:169], v[130:133], v[102:105], v[166:169]
	v_cvt_pk_bf16_f32 v120, v126, v127
	v_cvt_pk_bf16_f32 v121, v128, v129
	s_waitcnt lgkmcnt(5)
	v_mfma_f32_32x32x16_bf16 v[98:113], v[238:241], v[134:137], 0
	ds_read_b128 v[238:241], v250 offset:13888
	v_exp_f32_e32 v66, v66
	v_exp_f32_e32 v67, v67
	v_exp_f32_e32 v68, v68
	v_mfma_f32_32x32x16_bf16 v[34:49], v[182:185], v[118:121], v[34:49]
	v_exp_f32_e32 v69, v69
	v_exp_f32_e32 v70, v70
	v_exp_f32_e32 v71, v71
	v_mfma_f32_32x32x16_bf16 v[50:65], v[186:189], v[118:121], v[50:65]
	ds_read_b64_tr_b16 v[182:183], v252 offset:15360
	ds_read_b64_tr_b16 v[184:185], v252 offset:16896
	ds_read_b64_tr_b16 v[186:187], v252 offset:15424
	ds_read_b64_tr_b16 v[188:189], v252 offset:16960
	v_exp_f32_e32 v72, v72
	v_exp_f32_e32 v73, v73
	v_cvt_pk_bf16_f32 v66, v66, v67
	v_cvt_pk_bf16_f32 v67, v68, v69
	v_mfma_f32_16x16x32_bf16 v[170:173], v[130:133], v[118:121], v[170:173]
	v_cvt_pk_bf16_f32 v68, v70, v71
	v_cvt_pk_bf16_f32 v69, v72, v73
	s_waitcnt lgkmcnt(5)
	v_mfma_f32_32x32x16_bf16 v[98:113], v[242:245], v[138:141], v[98:113]
	ds_read_b128 v[242:245], v250 offset:13920
	v_exp_f32_e32 v82, v82
	v_exp_f32_e32 v83, v83
	v_exp_f32_e32 v84, v84
	v_mfma_f32_32x32x16_bf16 v[2:17], v[174:177], v[66:69], v[2:17]
	v_exp_f32_e32 v85, v85
	v_exp_f32_e32 v86, v86
	v_exp_f32_e32 v87, v87
	v_mfma_f32_32x32x16_bf16 v[18:33], v[178:181], v[66:69], v[18:33]
	v_exp_f32_e32 v88, v88
	v_exp_f32_e32 v89, v89
	v_cvt_pk_bf16_f32 v82, v82, v83
	v_cvt_pk_bf16_f32 v83, v84, v85
	v_mfma_f32_16x16x32_bf16 v[166:169], v[130:133], v[66:69], v[166:169]
	v_cvt_pk_bf16_f32 v84, v86, v87
	v_cvt_pk_bf16_f32 v85, v88, v89
	s_barrier
	s_waitcnt lgkmcnt(5)
	v_mfma_f32_32x32x16_bf16 v[114:129], v[238:241], v[142:145], 0
	ds_read_b128 v[238:241], v251
	v_exp_f32_e32 v74, v74
	v_exp_f32_e32 v75, v75
	v_exp_f32_e32 v76, v76
	v_mfma_f32_32x32x16_bf16 v[34:49], v[174:177], v[82:85], v[34:49]
	v_exp_f32_e32 v77, v77
	v_exp_f32_e32 v78, v78
	v_exp_f32_e32 v79, v79
	v_mfma_f32_32x32x16_bf16 v[50:65], v[178:181], v[82:85], v[50:65]
	ds_read_b64_tr_b16 v[174:175], v252 offset:18432
	ds_read_b64_tr_b16 v[176:177], v252 offset:19968
	ds_read_b64_tr_b16 v[178:179], v252 offset:18496
	ds_read_b64_tr_b16 v[180:181], v252 offset:20032
	v_exp_f32_e32 v80, v80
	v_exp_f32_e32 v81, v81
	v_cvt_pk_bf16_f32 v70, v74, v75
	v_cvt_pk_bf16_f32 v71, v76, v77
	v_mfma_f32_16x16x32_bf16 v[170:173], v[130:133], v[82:85], v[170:173]
	v_cvt_pk_bf16_f32 v72, v78, v79
	v_cvt_pk_bf16_f32 v73, v80, v81
	s_waitcnt lgkmcnt(5)
	v_mfma_f32_32x32x16_bf16 v[114:129], v[242:245], v[146:149], v[114:129]
	ds_read_b128 v[242:245], v251 offset:32
	v_exp_f32_e32 v90, v90
	v_exp_f32_e32 v91, v91
	v_exp_f32_e32 v92, v92
	v_mfma_f32_32x32x16_bf16 v[2:17], v[182:185], v[70:73], v[2:17]
	v_exp_f32_e32 v93, v93
	v_exp_f32_e32 v94, v94
	v_exp_f32_e32 v95, v95
	v_mfma_f32_32x32x16_bf16 v[18:33], v[186:189], v[70:73], v[18:33]
	v_exp_f32_e32 v96, v96
	v_exp_f32_e32 v97, v97
	v_cvt_pk_bf16_f32 v86, v90, v91
	v_cvt_pk_bf16_f32 v87, v92, v93
	v_mfma_f32_16x16x32_bf16 v[166:169], v[130:133], v[70:73], v[166:169]
	v_cvt_pk_bf16_f32 v88, v94, v95
	v_cvt_pk_bf16_f32 v89, v96, v97
	s_waitcnt lgkmcnt(5)
	v_mfma_f32_32x32x16_bf16 v[66:81], v[238:241], v[134:137], 0
	ds_read_b128 v[238:241], v251 offset:64
	v_exp_f32_e32 v98, v98
	v_exp_f32_e32 v99, v99
	v_exp_f32_e32 v100, v100
	v_mfma_f32_32x32x16_bf16 v[34:49], v[182:185], v[86:89], v[34:49]
	v_exp_f32_e32 v101, v101
	v_exp_f32_e32 v102, v102
	v_exp_f32_e32 v103, v103
	v_mfma_f32_32x32x16_bf16 v[50:65], v[186:189], v[86:89], v[50:65]
	ds_read_b64_tr_b16 v[182:183], v252 offset:21504
	ds_read_b64_tr_b16 v[184:185], v252 offset:23040
	ds_read_b64_tr_b16 v[186:187], v252 offset:21568
	ds_read_b64_tr_b16 v[188:189], v252 offset:23104
	v_exp_f32_e32 v104, v104
	v_exp_f32_e32 v105, v105
	v_cvt_pk_bf16_f32 v98, v98, v99
	v_cvt_pk_bf16_f32 v99, v100, v101
	v_mfma_f32_16x16x32_bf16 v[170:173], v[130:133], v[86:89], v[170:173]
	v_cvt_pk_bf16_f32 v100, v102, v103
	v_cvt_pk_bf16_f32 v101, v104, v105
	s_waitcnt lgkmcnt(5)
	v_mfma_f32_32x32x16_bf16 v[66:81], v[242:245], v[138:141], v[66:81]
	ds_read_b128 v[242:245], v251 offset:96
	v_exp_f32_e32 v114, v114
	v_exp_f32_e32 v115, v115
	v_exp_f32_e32 v116, v116
	v_mfma_f32_32x32x16_bf16 v[2:17], v[174:177], v[98:101], v[2:17]
	v_exp_f32_e32 v117, v117
	v_exp_f32_e32 v118, v118
	v_exp_f32_e32 v119, v119
	v_mfma_f32_32x32x16_bf16 v[18:33], v[178:181], v[98:101], v[18:33]
	v_exp_f32_e32 v120, v120
	v_exp_f32_e32 v121, v121
	v_cvt_pk_bf16_f32 v114, v114, v115
	v_cvt_pk_bf16_f32 v115, v116, v117
	v_mfma_f32_16x16x32_bf16 v[166:169], v[130:133], v[98:101], v[166:169]
	v_cvt_pk_bf16_f32 v116, v118, v119
	v_cvt_pk_bf16_f32 v117, v120, v121
	s_waitcnt lgkmcnt(5)
	v_mfma_f32_32x32x16_bf16 v[82:97], v[238:241], v[142:145], 0
	ds_read_b128 v[238:241], v251 offset:4608
	v_exp_f32_e32 v106, v106
	v_exp_f32_e32 v107, v107
	v_exp_f32_e32 v108, v108
	v_mfma_f32_32x32x16_bf16 v[34:49], v[174:177], v[114:117], v[34:49]
	v_exp_f32_e32 v109, v109
	v_exp_f32_e32 v110, v110
	v_exp_f32_e32 v111, v111
	v_mfma_f32_32x32x16_bf16 v[50:65], v[178:181], v[114:117], v[50:65]
	ds_read_b64_tr_b16 v[174:175], v215
	ds_read_b64_tr_b16 v[176:177], v215 offset:1536
	ds_read_b64_tr_b16 v[178:179], v215 offset:64
	ds_read_b64_tr_b16 v[180:181], v215 offset:1600
	v_exp_f32_e32 v112, v112
	v_exp_f32_e32 v113, v113
	v_cvt_pk_bf16_f32 v102, v106, v107
	v_cvt_pk_bf16_f32 v103, v108, v109
	v_mfma_f32_16x16x32_bf16 v[170:173], v[130:133], v[114:117], v[170:173]
	v_cvt_pk_bf16_f32 v104, v110, v111
	v_cvt_pk_bf16_f32 v105, v112, v113
	s_waitcnt lgkmcnt(5)
	v_mfma_f32_32x32x16_bf16 v[82:97], v[242:245], v[146:149], v[82:97]
	ds_read_b128 v[242:245], v251 offset:4640
	v_exp_f32_e32 v122, v122
	v_exp_f32_e32 v123, v123
	v_exp_f32_e32 v124, v124
	v_mfma_f32_32x32x16_bf16 v[2:17], v[182:185], v[102:105], v[2:17]
	v_exp_f32_e32 v125, v125
	v_exp_f32_e32 v126, v126
	v_exp_f32_e32 v127, v127
	v_mfma_f32_32x32x16_bf16 v[18:33], v[186:189], v[102:105], v[18:33]
	v_exp_f32_e32 v128, v128
	v_exp_f32_e32 v129, v129
	v_cvt_pk_bf16_f32 v118, v122, v123
	v_cvt_pk_bf16_f32 v119, v124, v125
	v_mfma_f32_16x16x32_bf16 v[166:169], v[130:133], v[102:105], v[166:169]
	v_cvt_pk_bf16_f32 v120, v126, v127
	v_cvt_pk_bf16_f32 v121, v128, v129
	s_cmp_lg_u32 s14, s10
	s_cbranch_scc1 .Latt_loop
	s_waitcnt lgkmcnt(0)
	s_nop 1
	v_mfma_f32_16x16x32_bf16 v[170:173], v[130:133], v[118:121], v[170:173]
	v_mfma_f32_32x32x16_bf16 v[34:49], v[182:185], v[118:121], v[34:49]
	v_mfma_f32_32x32x16_bf16 v[50:65], v[186:189], v[118:121], v[50:65]
	s_nop 11
	global_load_dwordx4 v[98:101], v[212:213], off offset:32
	global_load_dwordx4 v[102:105], v[212:213], off offset:64
	global_load_dwordx4 v[106:109], v[212:213], off offset:96
	global_load_dwordx4 v[110:113], v[212:213], off offset:128
	global_load_dwordx4 v[114:117], v[212:213], off offset:160
	global_load_dwordx4 v[122:125], v[212:213], off offset:192
	global_load_dwordx4 v[126:129], v[212:213], off offset:224
	ds_bpermute_b32 v66, v237, v166
	s_nop 3
	ds_bpermute_b32 v67, v237, v170
	s_lshl_b32 s64, s9, 1
	v_mov_b32_e32 v215, v191
	s_mov_b32 s2, 0xf226000
	s_waitcnt lgkmcnt(1)
	v_div_scale_f32 v68, s[10:11], v66, v66, 1.0
	v_rcp_f32_e32 v69, v68
	s_add_i32 s8, s8, 1
	s_cmp_eq_u32 s8, s7
	v_fma_f32 v70, -v68, v69, 1.0
	v_fmac_f32_e32 v69, v70, v69
	v_div_scale_f32 v70, vcc, 1.0, v66, 1.0
	v_mul_f32_e32 v71, v70, v69
	v_fma_f32 v72, -v68, v71, v70
	v_fmac_f32_e32 v71, v72, v69
	v_fma_f32 v68, -v68, v71, v70
	v_div_fmas_f32 v68, v68, v69, v71
	v_div_fixup_f32 v66, v68, v66, 1.0
	s_waitcnt lgkmcnt(0)
	v_div_scale_f32 v68, s[10:11], v67, v67, v230
	v_rcp_f32_e32 v69, v68
	s_mov_b64 s[10:11], 0xf226400
	v_fma_f32 v70, -v68, v69, 1.0
	v_fmac_f32_e32 v69, v70, v69
	v_div_scale_f32 v70, vcc, v230, v67, v230
	v_mul_f32_e32 v71, v70, v69
	v_fma_f32 v72, -v68, v71, v70
	v_fmac_f32_e32 v71, v72, v69
	v_fma_f32 v68, -v68, v71, v70
	v_div_fmas_f32 v68, v68, v69, v71
	v_div_fixup_f32 v68, v68, v67, v230
	v_pk_mul_f32 v[62:63], v[62:63], v[68:69] op_sel_hi:[1,0]
	v_pk_mul_f32 v[34:35], v[34:35], v[68:69] op_sel_hi:[1,0]
	v_pk_fma_f32 v[30:31], v[30:31], v[66:67], v[62:63] op_sel_hi:[1,0,1] neg_lo:[0,0,1] neg_hi:[0,0,1]
	v_pk_mul_f32 v[62:63], v[64:65], v[68:69] op_sel_hi:[1,0]
	v_pk_mul_f32 v[36:37], v[36:37], v[68:69] op_sel_hi:[1,0]
	v_pk_fma_f32 v[32:33], v[32:33], v[66:67], v[62:63] op_sel_hi:[1,0,1] neg_lo:[0,0,1] neg_hi:[0,0,1]
	v_lshlrev_b64 v[62:63], 11, v[216:217]
	v_lshl_add_u64 v[62:63], s[54:55], 0, v[62:63]
	v_lshl_add_u64 v[74:75], v[62:63], 0, s[64:65]
	global_load_dwordx4 v[62:65], v[212:213], off
	v_pk_fma_f32 v[34:35], v[2:3], v[66:67], v[34:35] op_sel_hi:[1,0,1] neg_lo:[0,0,1] neg_hi:[0,0,1]
	v_pk_fma_f32 v[4:5], v[4:5], v[66:67], v[36:37] op_sel_hi:[1,0,1] neg_lo:[0,0,1] neg_hi:[0,0,1]
	v_pk_mul_f32 v[76:77], v[34:35], v[34:35]
	v_pk_mul_f32 v[40:41], v[40:41], v[68:69] op_sel_hi:[1,0]
	v_pk_mul_f32 v[38:39], v[38:39], v[68:69] op_sel_hi:[1,0]
	v_pk_mul_f32 v[44:45], v[44:45], v[68:69] op_sel_hi:[1,0]
	v_pk_mul_f32 v[42:43], v[42:43], v[68:69] op_sel_hi:[1,0]
	v_pk_mul_f32 v[48:49], v[48:49], v[68:69] op_sel_hi:[1,0]
	v_pk_mul_f32 v[46:47], v[46:47], v[68:69] op_sel_hi:[1,0]
	v_pk_mul_f32 v[52:53], v[52:53], v[68:69] op_sel_hi:[1,0]
	v_pk_mul_f32 v[50:51], v[50:51], v[68:69] op_sel_hi:[1,0]
	v_pk_mul_f32 v[56:57], v[56:57], v[68:69] op_sel_hi:[1,0]
	v_pk_mul_f32 v[54:55], v[54:55], v[68:69] op_sel_hi:[1,0]
	v_pk_mul_f32 v[60:61], v[60:61], v[68:69] op_sel_hi:[1,0]
	v_pk_mul_f32 v[58:59], v[58:59], v[68:69] op_sel_hi:[1,0]
	v_pk_mul_f32 v[36:37], v[4:5], v[4:5]
	v_pk_fma_f32 v[8:9], v[8:9], v[66:67], v[40:41] op_sel_hi:[1,0,1] neg_lo:[0,0,1] neg_hi:[0,0,1]
	v_pk_fma_f32 v[38:39], v[6:7], v[66:67], v[38:39] op_sel_hi:[1,0,1] neg_lo:[0,0,1] neg_hi:[0,0,1]
	v_pk_fma_f32 v[12:13], v[12:13], v[66:67], v[44:45] op_sel_hi:[1,0,1] neg_lo:[0,0,1] neg_hi:[0,0,1]
	v_pk_fma_f32 v[10:11], v[10:11], v[66:67], v[42:43] op_sel_hi:[1,0,1] neg_lo:[0,0,1] neg_hi:[0,0,1]
	v_pk_fma_f32 v[16:17], v[16:17], v[66:67], v[48:49] op_sel_hi:[1,0,1] neg_lo:[0,0,1] neg_hi:[0,0,1]
	v_pk_fma_f32 v[14:15], v[14:15], v[66:67], v[46:47] op_sel_hi:[1,0,1] neg_lo:[0,0,1] neg_hi:[0,0,1]
	v_pk_fma_f32 v[20:21], v[20:21], v[66:67], v[52:53] op_sel_hi:[1,0,1] neg_lo:[0,0,1] neg_hi:[0,0,1]
	v_pk_fma_f32 v[18:19], v[18:19], v[66:67], v[50:51] op_sel_hi:[1,0,1] neg_lo:[0,0,1] neg_hi:[0,0,1]
	v_pk_fma_f32 v[24:25], v[24:25], v[66:67], v[56:57] op_sel_hi:[1,0,1] neg_lo:[0,0,1] neg_hi:[0,0,1]
	v_pk_fma_f32 v[22:23], v[22:23], v[66:67], v[54:55] op_sel_hi:[1,0,1] neg_lo:[0,0,1] neg_hi:[0,0,1]
	v_pk_fma_f32 v[28:29], v[28:29], v[66:67], v[60:61] op_sel_hi:[1,0,1] neg_lo:[0,0,1] neg_hi:[0,0,1]
	v_pk_fma_f32 v[26:27], v[26:27], v[66:67], v[58:59] op_sel_hi:[1,0,1] neg_lo:[0,0,1] neg_hi:[0,0,1]
	v_add_f32_e32 v66, v76, v77
	v_add_f32_e32 v36, v36, v66
	v_pk_mul_f32 v[6:7], v[38:39], v[38:39]
	v_add_f32_e32 v36, v37, v36
	v_add_f32_e32 v6, v6, v36
	v_pk_mul_f32 v[40:41], v[8:9], v[8:9]
	v_add_f32_e32 v6, v7, v6
	v_add_f32_e32 v6, v40, v6
	v_pk_mul_f32 v[42:43], v[10:11], v[10:11]
	v_add_f32_e32 v6, v41, v6
	v_add_f32_e32 v6, v42, v6
	v_pk_mul_f32 v[44:45], v[12:13], v[12:13]
	v_add_f32_e32 v6, v43, v6
	v_add_f32_e32 v6, v44, v6
	v_pk_mul_f32 v[46:47], v[14:15], v[14:15]
	v_add_f32_e32 v6, v45, v6
	v_add_f32_e32 v6, v46, v6
	v_pk_mul_f32 v[48:49], v[16:17], v[16:17]
	v_add_f32_e32 v6, v47, v6
	v_add_f32_e32 v6, v48, v6
	v_pk_mul_f32 v[50:51], v[18:19], v[18:19]
	v_add_f32_e32 v6, v49, v6
	v_add_f32_e32 v6, v50, v6
	v_pk_mul_f32 v[52:53], v[20:21], v[20:21]
	v_add_f32_e32 v6, v51, v6
	v_add_f32_e32 v6, v52, v6
	v_pk_mul_f32 v[54:55], v[22:23], v[22:23]
	v_add_f32_e32 v6, v53, v6
	v_add_f32_e32 v6, v54, v6
	v_pk_mul_f32 v[56:57], v[24:25], v[24:25]
	v_add_f32_e32 v6, v55, v6
	v_add_f32_e32 v6, v56, v6
	v_pk_mul_f32 v[58:59], v[26:27], v[26:27]
	v_add_f32_e32 v6, v57, v6
	v_add_f32_e32 v6, v58, v6
	v_pk_mul_f32 v[60:61], v[28:29], v[28:29]
	v_add_f32_e32 v6, v59, v6
	v_add_f32_e32 v6, v60, v6
	v_pk_mul_f32 v[70:71], v[30:31], v[30:31]
	v_add_f32_e32 v6, v61, v6
	v_add_f32_e32 v6, v70, v6
	v_pk_mul_f32 v[72:73], v[32:33], v[32:33]
	v_add_f32_e32 v6, v71, v6
	v_add_f32_e32 v6, v72, v6
	v_add_f32_e32 v6, v73, v6
	ds_bpermute_b32 v7, v229, v6
	v_lshl_add_u64 v[74:75], v[74:75], 0, v[214:215]
	v_lshl_add_u64 v[2:3], v[74:75], 0, s[10:11]
	s_waitcnt lgkmcnt(0)
	v_add_f32_e32 v6, v6, v7
	v_fmamk_f32 v6, v6, 0x3c800000, v192
	v_cmp_gt_f32_e32 vcc, s70, v6
	v_mul_f32_e32 v7, 0x4b800000, v6
	s_nop 0
	v_cndmask_b32_e32 v6, v6, v7, vcc
	v_rsq_f32_e32 v6, v6
	s_nop 0
	v_mul_f32_e32 v7, 0x45800000, v6
	v_cndmask_b32_e32 v6, v6, v7, vcc
	v_mul_f32_e32 v36, v233, v6
	v_pk_mul_f32 v[6:7], v[34:35], v[36:37] op_sel_hi:[1,0]
	v_pk_mul_f32 v[4:5], v[4:5], v[36:37] op_sel_hi:[1,0]
	s_waitcnt vmcnt(0)
	v_pk_mul_f32 v[6:7], v[62:63], v[6:7]
	v_pk_mul_f32 v[4:5], v[64:65], v[4:5]
	v_cvt_pk_bf16_f32 v6, v6, v7
	v_cvt_pk_bf16_f32 v7, v4, v5
	v_add_co_u32_e32 v4, vcc, s2, v74
	v_pk_mul_f32 v[34:35], v[38:39], v[36:37] op_sel_hi:[1,0]
	s_nop 0
	v_addc_co_u32_e32 v5, vcc, 0, v75, vcc
	global_store_dwordx2 v[4:5], v[6:7], off offset:1024
	v_pk_mul_f32 v[8:9], v[8:9], v[36:37] op_sel_hi:[1,0]
	v_mov_b64_e32 v[4:5], v[98:99]
	v_mov_b64_e32 v[6:7], v[100:101]
	v_pk_mul_f32 v[4:5], v[4:5], v[34:35]
	v_pk_mul_f32 v[6:7], v[6:7], v[8:9]
	v_cvt_pk_bf16_f32 v4, v4, v5
	v_cvt_pk_bf16_f32 v5, v6, v7
	global_store_dwordx2 v[2:3], v[4:5], off offset:16
	v_pk_mul_f32 v[8:9], v[10:11], v[36:37] op_sel_hi:[1,0]
	v_mov_b64_e32 v[4:5], v[102:103]
	v_mov_b64_e32 v[6:7], v[104:105]
	v_pk_mul_f32 v[4:5], v[4:5], v[8:9]
	v_pk_mul_f32 v[8:9], v[12:13], v[36:37] op_sel_hi:[1,0]
	v_cvt_pk_bf16_f32 v4, v4, v5
	v_pk_mul_f32 v[6:7], v[6:7], v[8:9]
	v_pk_mul_f32 v[8:9], v[14:15], v[36:37] op_sel_hi:[1,0]
	v_cvt_pk_bf16_f32 v5, v6, v7
	global_store_dwordx2 v[2:3], v[4:5], off offset:32
	v_mov_b64_e32 v[4:5], v[106:107]
	v_mov_b64_e32 v[6:7], v[108:109]
	v_pk_mul_f32 v[4:5], v[4:5], v[8:9]
	v_pk_mul_f32 v[8:9], v[16:17], v[36:37] op_sel_hi:[1,0]
	v_cvt_pk_bf16_f32 v4, v4, v5
	v_pk_mul_f32 v[6:7], v[6:7], v[8:9]
	v_pk_mul_f32 v[8:9], v[18:19], v[36:37] op_sel_hi:[1,0]
	v_cvt_pk_bf16_f32 v5, v6, v7
	global_store_dwordx2 v[2:3], v[4:5], off offset:48
	v_mov_b64_e32 v[4:5], v[110:111]
	v_mov_b64_e32 v[6:7], v[112:113]
	v_pk_mul_f32 v[4:5], v[4:5], v[8:9]
	v_pk_mul_f32 v[8:9], v[20:21], v[36:37] op_sel_hi:[1,0]
	v_cvt_pk_bf16_f32 v4, v4, v5
	v_pk_mul_f32 v[6:7], v[6:7], v[8:9]
	v_pk_mul_f32 v[8:9], v[22:23], v[36:37] op_sel_hi:[1,0]
	v_cvt_pk_bf16_f32 v5, v6, v7
	global_store_dwordx2 v[2:3], v[4:5], off offset:64
	v_mov_b64_e32 v[4:5], v[114:115]
	v_mov_b64_e32 v[6:7], v[116:117]
	v_pk_mul_f32 v[4:5], v[4:5], v[8:9]
	v_pk_mul_f32 v[8:9], v[24:25], v[36:37] op_sel_hi:[1,0]
	v_cvt_pk_bf16_f32 v4, v4, v5
	v_pk_mul_f32 v[6:7], v[6:7], v[8:9]
	v_pk_mul_f32 v[8:9], v[26:27], v[36:37] op_sel_hi:[1,0]
	v_cvt_pk_bf16_f32 v5, v6, v7
	global_store_dwordx2 v[2:3], v[4:5], off offset:80
	v_mov_b64_e32 v[4:5], v[122:123]
	v_mov_b64_e32 v[6:7], v[124:125]
	v_pk_mul_f32 v[4:5], v[4:5], v[8:9]
	v_pk_mul_f32 v[8:9], v[28:29], v[36:37] op_sel_hi:[1,0]
	v_cvt_pk_bf16_f32 v4, v4, v5
	v_pk_mul_f32 v[6:7], v[6:7], v[8:9]
	v_pk_mul_f32 v[8:9], v[30:31], v[36:37] op_sel_hi:[1,0]
	v_cvt_pk_bf16_f32 v5, v6, v7
	global_store_dwordx2 v[2:3], v[4:5], off offset:96
	v_mov_b64_e32 v[4:5], v[126:127]
	v_mov_b64_e32 v[6:7], v[128:129]
	v_pk_mul_f32 v[4:5], v[4:5], v[8:9]
	v_pk_mul_f32 v[8:9], v[32:33], v[36:37] op_sel_hi:[1,0]
	v_cvt_pk_bf16_f32 v4, v4, v5
	v_pk_mul_f32 v[6:7], v[6:7], v[8:9]
	s_nop 0
	v_cvt_pk_bf16_f32 v5, v6, v7
	global_store_dwordx2 v[2:3], v[4:5], off offset:112
	s_cbranch_scc0 .LBB0_745

	.amdhsa_kernel _Z14fwd_megakernel4Args
		.amdhsa_group_segment_fixed_size 0
		.amdhsa_private_segment_fixed_size 0
		.amdhsa_kernarg_size 544
		.amdhsa_user_sgpr_count 2
		.amdhsa_user_sgpr_dispatch_ptr 0
		.amdhsa_user_sgpr_queue_ptr 0
		.amdhsa_user_sgpr_kernarg_segment_ptr 1
		.amdhsa_user_sgpr_dispatch_id 0
		.amdhsa_user_sgpr_kernarg_preload_length 0
		.amdhsa_user_sgpr_kernarg_preload_offset 0
		.amdhsa_user_sgpr_private_segment_size 0
		.amdhsa_uses_dynamic_stack 0
		.amdhsa_enable_private_segment 0
		.amdhsa_system_sgpr_workgroup_id_x 1
		.amdhsa_system_sgpr_workgroup_id_y 0
		.amdhsa_system_sgpr_workgroup_id_z 0
		.amdhsa_system_sgpr_workgroup_info 0
		.amdhsa_system_vgpr_workitem_id 0
		.amdhsa_next_free_vgpr 254
		.amdhsa_next_free_sgpr 102
		.amdhsa_accum_offset 256
		.amdhsa_reserve_vcc 1
		.amdhsa_float_round_mode_32 0
		.amdhsa_float_round_mode_16_64 0
		.amdhsa_float_denorm_mode_32 3
		.amdhsa_float_denorm_mode_16_64 3
		.amdhsa_dx10_clamp 1
		.amdhsa_ieee_mode 1
		.amdhsa_fp16_overflow 0
		.amdhsa_tg_split 0
		.amdhsa_exception_fp_ieee_invalid_op 0
		.amdhsa_exception_fp_denorm_src 0
		.amdhsa_exception_fp_ieee_div_zero 0
		.amdhsa_exception_fp_ieee_overflow 0
		.amdhsa_exception_fp_ieee_underflow 0
		.amdhsa_exception_fp_ieee_inexact 0
		.amdhsa_exception_int_div_zero 0
	.end_amdhsa_kernel

amdhsa.kernels:
  - .agpr_count:     0
    .args:
      - .offset:         0
        .size:           288
        .value_kind:     by_value
      - .offset:         288
        .size:           4
        .value_kind:     hidden_block_count_x
      - .offset:         292
        .size:           4
        .value_kind:     hidden_block_count_y
      - .offset:         296
        .size:           4
        .value_kind:     hidden_block_count_z
      - .offset:         300
        .size:           2
        .value_kind:     hidden_group_size_x
      - .offset:         302
        .size:           2
        .value_kind:     hidden_group_size_y
      - .offset:         304
        .size:           2
        .value_kind:     hidden_group_size_z
      - .offset:         306
        .size:           2
        .value_kind:     hidden_remainder_x
      - .offset:         308
        .size:           2
        .value_kind:     hidden_remainder_y
      - .offset:         310
        .size:           2
        .value_kind:     hidden_remainder_z
      - .offset:         328
        .size:           8
        .value_kind:     hidden_global_offset_x
      - .offset:         336
        .size:           8
        .value_kind:     hidden_global_offset_y
      - .offset:         344
        .size:           8
        .value_kind:     hidden_global_offset_z
      - .offset:         352
        .size:           2
        .value_kind:     hidden_grid_dims
      - .offset:         408
        .size:           4
        .value_kind:     hidden_dynamic_lds_size
    .group_segment_fixed_size: 0
    .kernarg_segment_align: 8
    .kernarg_segment_size: 544
    .language:       OpenCL C
    .language_version:
      - 2
      - 0
    .max_flat_workgroup_size: 512
    .name:           _Z14fwd_megakernel4Args
    .private_segment_fixed_size: 0
    .sgpr_count:     108
    .sgpr_spill_count: 70
    .symbol:         _Z14fwd_megakernel4Args.kd
    .uniform_work_group_size: 1
    .uses_dynamic_stack: false
    .vgpr_count:     254
    .vgpr_spill_count: 0
    .wavefront_size: 64
